# code placement: .p2align 6 on the 9 GEMM K-loop heads (64B-aligned loop entry), on top of v14
# speedup vs baseline: 1.0146x; 1.0006x over previous
; template <class Epi, bool HALO>
; __device__ __forceinline__ void gemm_phase(LAS unsigned char* lds, const Gemm g, const StaticOrder& S, const Epi& E) {
;     ...
;         const char* nA = has_next ? A0 + (size_t)nxt.pm * tstepA + (size_t)nxt.pn * g.a_pn_off * 2 : cA; const char* nB = has_next ? (const char*)g.Bt + (size_t)nxt.pn * tstepB : cB;
;         for (int t = 0; t < nt; t += 2) {
;     ...
; #pragma unroll
;         for (int a = 0; a < 2; ++a)
; #pragma unroll
;             for (int b = 0; b < 2; ++b)
; #pragma unroll
;                 for (int m = 0; m < 4; ++m)
; #pragma unroll
;                     for (int n = 0; n < 2; ++n) acc[a][b][m][n] = (f32x4){0.f, 0.f, 0.f, 0.f};
;         cur = nxt; cA = nA; cB = nB; ++ui;
.LBB0_216:
	s_ashr_i32 s27, s26, 31
	s_lshl_b64 s[28:29], s[26:27], 19
	s_add_u32 s28, s54, s28
	s_addc_u32 s29, s55, s29
	s_and_b64 s[30:31], s[6:7], exec
	s_cselect_b32 s27, s29, s39
	s_cselect_b32 s35, s28, s38
	s_ashr_i32 s25, s24, 31
	s_lshl_b64 s[30:31], s[24:25], 19
	s_add_u32 s30, s52, s30
	s_addc_u32 s31, s53, s31
	s_and_b64 s[40:41], s[6:7], exec
	s_cselect_b32 s25, s31, s37
	s_cselect_b32 s86, s30, s36
	s_add_u32 s87, s36, 0x10000
	s_addc_u32 s88, s37, 0
	s_add_u32 s36, s38, 0x40080
	v_mov_b32_e32 v0, 0
	s_addc_u32 s37, s39, 0
	s_mov_b32 s89, -2
	v_mov_b32_e32 v1, v0
	v_mov_b32_e32 v2, v0
	v_mov_b32_e32 v3, v0
	v_mov_b32_e32 v4, v0
	v_mov_b32_e32 v5, v0
	v_mov_b32_e32 v6, v0
	v_mov_b32_e32 v7, v0
	v_mov_b32_e32 v16, v0
	v_mov_b32_e32 v17, v0
	v_mov_b32_e32 v18, v0
	v_mov_b32_e32 v19, v0
	v_mov_b32_e32 v20, v0
	v_mov_b32_e32 v21, v0
	v_mov_b32_e32 v22, v0
	v_mov_b32_e32 v23, v0
	v_mov_b32_e32 v32, v0
	v_mov_b32_e32 v33, v0
	v_mov_b32_e32 v34, v0
	v_mov_b32_e32 v35, v0
	v_mov_b32_e32 v36, v0
	v_mov_b32_e32 v37, v0
	v_mov_b32_e32 v38, v0
	v_mov_b32_e32 v39, v0
	v_mov_b32_e32 v48, v0
	v_mov_b32_e32 v49, v0
	v_mov_b32_e32 v50, v0
	v_mov_b32_e32 v51, v0
	v_mov_b32_e32 v52, v0
	v_mov_b32_e32 v53, v0
	v_mov_b32_e32 v54, v0
	v_mov_b32_e32 v55, v0
	v_mov_b32_e32 v8, v0
	v_mov_b32_e32 v9, v0
	v_mov_b32_e32 v10, v0
	v_mov_b32_e32 v11, v0
	v_mov_b32_e32 v12, v0
	v_mov_b32_e32 v13, v0
	v_mov_b32_e32 v14, v0
	v_mov_b32_e32 v15, v0
	v_mov_b32_e32 v24, v0
	v_mov_b32_e32 v25, v0
	v_mov_b32_e32 v26, v0
	v_mov_b32_e32 v27, v0
	v_mov_b32_e32 v28, v0
	v_mov_b32_e32 v29, v0
	v_mov_b32_e32 v30, v0
	v_mov_b32_e32 v31, v0
	v_mov_b32_e32 v40, v0
	v_mov_b32_e32 v41, v0
	v_mov_b32_e32 v42, v0
	v_mov_b32_e32 v43, v0
	v_mov_b32_e32 v44, v0
	v_mov_b32_e32 v45, v0
	v_mov_b32_e32 v46, v0
	v_mov_b32_e32 v47, v0
	v_mov_b32_e32 v56, v0
	v_mov_b32_e32 v57, v0
	v_mov_b32_e32 v58, v0
	v_mov_b32_e32 v59, v0
	v_mov_b32_e32 v60, v0
	v_mov_b32_e32 v61, v0
	v_mov_b32_e32 v62, v0
	v_mov_b32_e32 v63, v0
	v_mov_b32_e32 v64, v0
	v_mov_b32_e32 v65, v0
	v_mov_b32_e32 v66, v0
	v_mov_b32_e32 v67, v0
	v_mov_b32_e32 v68, v0
	v_mov_b32_e32 v69, v0
	v_mov_b32_e32 v70, v0
	v_mov_b32_e32 v71, v0
	v_mov_b32_e32 v80, v0
	v_mov_b32_e32 v81, v0
	v_mov_b32_e32 v82, v0
	v_mov_b32_e32 v83, v0
	v_mov_b32_e32 v84, v0
	v_mov_b32_e32 v85, v0
	v_mov_b32_e32 v86, v0
	v_mov_b32_e32 v87, v0
	v_mov_b32_e32 v96, v0
	v_mov_b32_e32 v97, v0
	v_mov_b32_e32 v98, v0
	v_mov_b32_e32 v99, v0
	v_mov_b32_e32 v100, v0
	v_mov_b32_e32 v101, v0
	v_mov_b32_e32 v102, v0
	v_mov_b32_e32 v103, v0
	v_mov_b32_e32 v112, v0
	v_mov_b32_e32 v113, v0
	v_mov_b32_e32 v114, v0
	v_mov_b32_e32 v115, v0
	v_mov_b32_e32 v116, v0
	v_mov_b32_e32 v117, v0
	v_mov_b32_e32 v118, v0
	v_mov_b32_e32 v119, v0
	v_mov_b32_e32 v72, v0
	v_mov_b32_e32 v73, v0
	v_mov_b32_e32 v74, v0
	v_mov_b32_e32 v75, v0
	v_mov_b32_e32 v76, v0
	v_mov_b32_e32 v77, v0
	v_mov_b32_e32 v78, v0
	v_mov_b32_e32 v79, v0
	v_mov_b32_e32 v88, v0
	v_mov_b32_e32 v89, v0
	v_mov_b32_e32 v90, v0
	v_mov_b32_e32 v91, v0
	v_mov_b32_e32 v92, v0
	v_mov_b32_e32 v93, v0
	v_mov_b32_e32 v94, v0
	v_mov_b32_e32 v95, v0
	v_mov_b32_e32 v104, v0
	v_mov_b32_e32 v105, v0
	v_mov_b32_e32 v106, v0
	v_mov_b32_e32 v107, v0
	v_mov_b32_e32 v108, v0
	v_mov_b32_e32 v109, v0
	v_mov_b32_e32 v110, v0
	v_mov_b32_e32 v111, v0
	v_mov_b32_e32 v120, v0
	v_mov_b32_e32 v121, v0
	v_mov_b32_e32 v122, v0
	v_mov_b32_e32 v123, v0
	v_mov_b32_e32 v124, v0
	v_mov_b32_e32 v125, v0
	v_mov_b32_e32 v126, v0
	v_mov_b32_e32 v127, v0
	.p2align	6

; template <class Epi, bool HALO>
; __device__ __forceinline__ void gemm_phase(LAS unsigned char* lds, const Gemm g, const StaticOrder& S, const Epi& E) {
;     ...
;         const bool has_next = S.next(ui + 1, nxt);
;         const char* nA = has_next ? A0 + (size_t)nxt.pm * tstepA + (size_t)nxt.pn * g.a_pn_off * 2 : cA; const char* nB = has_next ? (const char*)g.Bt + (size_t)nxt.pn * tstepB : cB;
;         for (int t = 0; t < nt; t += 2) {
.LBB0_411:
	s_add_u32 s16, s16, s3
	s_addc_u32 s17, s17, s60
	s_mov_b64 s[6:7], 0
	.p2align	6

; template <class Epi, bool HALO>
; __device__ __forceinline__ void gemm_phase(LAS unsigned char* lds, const Gemm g, const StaticOrder& S, const Epi& E) {
;     ...
;         const char* nA = has_next ? A0 + (size_t)nxt.pm * tstepA + (size_t)nxt.pn * g.a_pn_off * 2 : cA; const char* nB = has_next ? (const char*)g.Bt + (size_t)nxt.pn * tstepB : cB;
;         for (int t = 0; t < nt; t += 2) {
;     ...
; #pragma unroll
;         for (int a = 0; a < 2; ++a)
; #pragma unroll
;             for (int b = 0; b < 2; ++b)
; #pragma unroll
;                 for (int m = 0; m < 4; ++m)
; #pragma unroll
;                     for (int n = 0; n < 2; ++n) acc[a][b][m][n] = (f32x4){0.f, 0.f, 0.f, 0.f};
;         cur = nxt; cA = nA; cB = nB; ++ui;
.LBB0_498:
	s_ashr_i32 s23, s22, 31
	s_lshl_b64 s[24:25], s[22:23], 19
	s_add_u32 s24, s40, s24
	s_addc_u32 s25, s41, s25
	s_and_b64 s[26:27], s[6:7], exec
	s_cselect_b32 s23, s25, s37
	s_cselect_b32 s29, s24, s36
	s_ashr_i32 s21, s20, 31
	s_lshl_b64 s[26:27], s[20:21], 19
	s_add_u32 s26, s42, s26
	s_addc_u32 s27, s43, s27
	s_and_b64 s[38:39], s[6:7], exec
	s_cselect_b32 s21, s27, s35
	s_cselect_b32 s31, s26, s34
	s_add_u32 s64, s34, 0x10000
	s_addc_u32 s65, s35, 0
	s_add_u32 s34, s36, 0x40080
	v_mov_b32_e32 v0, 0
	s_addc_u32 s35, s37, 0
	s_mov_b32 s66, -2
	s_waitcnt lgkmcnt(0)
	v_mov_b32_e32 v1, v0
	v_mov_b32_e32 v2, v0
	v_mov_b32_e32 v3, v0
	v_mov_b32_e32 v4, v0
	v_mov_b32_e32 v5, v0
	v_mov_b32_e32 v6, v0
	v_mov_b32_e32 v7, v0
	v_mov_b32_e32 v16, v0
	v_mov_b32_e32 v17, v0
	v_mov_b32_e32 v18, v0
	v_mov_b32_e32 v19, v0
	v_mov_b32_e32 v20, v0
	v_mov_b32_e32 v21, v0
	v_mov_b32_e32 v22, v0
	v_mov_b32_e32 v23, v0
	v_mov_b32_e32 v32, v0
	v_mov_b32_e32 v33, v0
	v_mov_b32_e32 v34, v0
	v_mov_b32_e32 v35, v0
	v_mov_b32_e32 v36, v0
	v_mov_b32_e32 v37, v0
	v_mov_b32_e32 v38, v0
	v_mov_b32_e32 v39, v0
	v_mov_b32_e32 v48, v0
	v_mov_b32_e32 v49, v0
	v_mov_b32_e32 v50, v0
	v_mov_b32_e32 v51, v0
	v_mov_b32_e32 v52, v0
	v_mov_b32_e32 v53, v0
	v_mov_b32_e32 v54, v0
	v_mov_b32_e32 v55, v0
	v_mov_b32_e32 v8, v0
	v_mov_b32_e32 v9, v0
	v_mov_b32_e32 v10, v0
	v_mov_b32_e32 v11, v0
	v_mov_b32_e32 v12, v0
	v_mov_b32_e32 v13, v0
	v_mov_b32_e32 v14, v0
	v_mov_b32_e32 v15, v0
	v_mov_b32_e32 v24, v0
	v_mov_b32_e32 v25, v0
	v_mov_b32_e32 v26, v0
	v_mov_b32_e32 v27, v0
	v_mov_b32_e32 v28, v0
	v_mov_b32_e32 v29, v0
	v_mov_b32_e32 v30, v0
	v_mov_b32_e32 v31, v0
	v_mov_b32_e32 v40, v0
	v_mov_b32_e32 v41, v0
	v_mov_b32_e32 v42, v0
	v_mov_b32_e32 v43, v0
	v_mov_b32_e32 v44, v0
	v_mov_b32_e32 v45, v0
	v_mov_b32_e32 v46, v0
	v_mov_b32_e32 v47, v0
	v_mov_b32_e32 v56, v0
	v_mov_b32_e32 v57, v0
	v_mov_b32_e32 v58, v0
	v_mov_b32_e32 v59, v0
	v_mov_b32_e32 v60, v0
	v_mov_b32_e32 v61, v0
	v_mov_b32_e32 v62, v0
	v_mov_b32_e32 v63, v0
	v_mov_b32_e32 v64, v0
	v_mov_b32_e32 v65, v0
	v_mov_b32_e32 v66, v0
	v_mov_b32_e32 v67, v0
	v_mov_b32_e32 v68, v0
	v_mov_b32_e32 v69, v0
	v_mov_b32_e32 v70, v0
	v_mov_b32_e32 v71, v0
	v_mov_b32_e32 v80, v0
	v_mov_b32_e32 v81, v0
	v_mov_b32_e32 v82, v0
	v_mov_b32_e32 v83, v0
	v_mov_b32_e32 v84, v0
	v_mov_b32_e32 v85, v0
	v_mov_b32_e32 v86, v0
	v_mov_b32_e32 v87, v0
	v_mov_b32_e32 v96, v0
	v_mov_b32_e32 v97, v0
	v_mov_b32_e32 v98, v0
	v_mov_b32_e32 v99, v0
	v_mov_b32_e32 v100, v0
	v_mov_b32_e32 v101, v0
	v_mov_b32_e32 v102, v0
	v_mov_b32_e32 v103, v0
	v_mov_b32_e32 v112, v0
	v_mov_b32_e32 v113, v0
	v_mov_b32_e32 v114, v0
	v_mov_b32_e32 v115, v0
	v_mov_b32_e32 v116, v0
	v_mov_b32_e32 v117, v0
	v_mov_b32_e32 v118, v0
	v_mov_b32_e32 v119, v0
	v_mov_b32_e32 v72, v0
	v_mov_b32_e32 v73, v0
	v_mov_b32_e32 v74, v0
	v_mov_b32_e32 v75, v0
	v_mov_b32_e32 v76, v0
	v_mov_b32_e32 v77, v0
	v_mov_b32_e32 v78, v0
	v_mov_b32_e32 v79, v0
	v_mov_b32_e32 v88, v0
	v_mov_b32_e32 v89, v0
	v_mov_b32_e32 v90, v0
	v_mov_b32_e32 v91, v0
	v_mov_b32_e32 v92, v0
	v_mov_b32_e32 v93, v0
	v_mov_b32_e32 v94, v0
	v_mov_b32_e32 v95, v0
	v_mov_b32_e32 v104, v0
	v_mov_b32_e32 v105, v0
	v_mov_b32_e32 v106, v0
	v_mov_b32_e32 v107, v0
	v_mov_b32_e32 v108, v0
	v_mov_b32_e32 v109, v0
	v_mov_b32_e32 v110, v0
	v_mov_b32_e32 v111, v0
	v_mov_b32_e32 v120, v0
	v_mov_b32_e32 v121, v0
	v_mov_b32_e32 v122, v0
	v_mov_b32_e32 v123, v0
	v_mov_b32_e32 v124, v0
	v_mov_b32_e32 v125, v0
	v_mov_b32_e32 v126, v0
	v_mov_b32_e32 v127, v0
	.p2align	6

; template <class Epi, bool HALO>
; __device__ __forceinline__ void gemm_phase(LAS unsigned char* lds, const Gemm g, const StaticOrder& S, const Epi& E) {
;     ...
;         const bool has_next = S.next(ui + 1, nxt);
;         const char* nA = has_next ? A0 + (size_t)nxt.pm * tstepA + (size_t)nxt.pn * g.a_pn_off * 2 : cA; const char* nB = has_next ? (const char*)g.Bt + (size_t)nxt.pn * tstepB : cB;
;         for (int t = 0; t < nt; t += 2) {
.Lwp5_skip:
	.p2align	6

; template <class Epi, bool HALO>
; __device__ __forceinline__ void gemm_phase(LAS unsigned char* lds, const Gemm g, const StaticOrder& S, const Epi& E) {
;     ...
;         const char* nA = has_next ? A0 + (size_t)nxt.pm * tstepA + (size_t)nxt.pn * g.a_pn_off * 2 : cA; const char* nB = has_next ? (const char*)g.Bt + (size_t)nxt.pn * tstepB : cB;
;         for (int t = 0; t < nt; t += 2) {
;     ...
; #pragma unroll
;         for (int a = 0; a < 2; ++a)
; #pragma unroll
;             for (int b = 0; b < 2; ++b)
; #pragma unroll
;                 for (int m = 0; m < 4; ++m)
; #pragma unroll
;                     for (int n = 0; n < 2; ++n) acc[a][b][m][n] = (f32x4){0.f, 0.f, 0.f, 0.f};
;         cur = nxt; cA = nA; cB = nB; ++ui;
.LBB0_726:
	s_add_u32 s24, s24, 0xc000
	s_addc_u32 s25, s25, 0
	s_add_u32 s60, s26, 0x10000
	v_mov_b32_e32 v0, 0
	s_addc_u32 s61, s27, 0
	s_mov_b32 s62, -2
	s_waitcnt lgkmcnt(0)
	v_mov_b32_e32 v1, v0
	v_mov_b32_e32 v2, v0
	v_mov_b32_e32 v3, v0
	v_mov_b32_e32 v4, v0
	v_mov_b32_e32 v5, v0
	v_mov_b32_e32 v6, v0
	v_mov_b32_e32 v7, v0
	v_mov_b32_e32 v16, v0
	v_mov_b32_e32 v17, v0
	v_mov_b32_e32 v18, v0
	v_mov_b32_e32 v19, v0
	v_mov_b32_e32 v20, v0
	v_mov_b32_e32 v21, v0
	v_mov_b32_e32 v22, v0
	v_mov_b32_e32 v23, v0
	v_mov_b32_e32 v32, v0
	v_mov_b32_e32 v33, v0
	v_mov_b32_e32 v34, v0
	v_mov_b32_e32 v35, v0
	v_mov_b32_e32 v36, v0
	v_mov_b32_e32 v37, v0
	v_mov_b32_e32 v38, v0
	v_mov_b32_e32 v39, v0
	v_mov_b32_e32 v48, v0
	v_mov_b32_e32 v49, v0
	v_mov_b32_e32 v50, v0
	v_mov_b32_e32 v51, v0
	v_mov_b32_e32 v52, v0
	v_mov_b32_e32 v53, v0
	v_mov_b32_e32 v54, v0
	v_mov_b32_e32 v55, v0
	v_mov_b32_e32 v8, v0
	v_mov_b32_e32 v9, v0
	v_mov_b32_e32 v10, v0
	v_mov_b32_e32 v11, v0
	v_mov_b32_e32 v12, v0
	v_mov_b32_e32 v13, v0
	v_mov_b32_e32 v14, v0
	v_mov_b32_e32 v15, v0
	v_mov_b32_e32 v24, v0
	v_mov_b32_e32 v25, v0
	v_mov_b32_e32 v26, v0
	v_mov_b32_e32 v27, v0
	v_mov_b32_e32 v28, v0
	v_mov_b32_e32 v29, v0
	v_mov_b32_e32 v30, v0
	v_mov_b32_e32 v31, v0
	v_mov_b32_e32 v40, v0
	v_mov_b32_e32 v41, v0
	v_mov_b32_e32 v42, v0
	v_mov_b32_e32 v43, v0
	v_mov_b32_e32 v44, v0
	v_mov_b32_e32 v45, v0
	v_mov_b32_e32 v46, v0
	v_mov_b32_e32 v47, v0
	v_mov_b32_e32 v56, v0
	v_mov_b32_e32 v57, v0
	v_mov_b32_e32 v58, v0
	v_mov_b32_e32 v59, v0
	v_mov_b32_e32 v60, v0
	v_mov_b32_e32 v61, v0
	v_mov_b32_e32 v62, v0
	v_mov_b32_e32 v63, v0
	v_mov_b32_e32 v64, v0
	v_mov_b32_e32 v65, v0
	v_mov_b32_e32 v66, v0
	v_mov_b32_e32 v67, v0
	v_mov_b32_e32 v68, v0
	v_mov_b32_e32 v69, v0
	v_mov_b32_e32 v70, v0
	v_mov_b32_e32 v71, v0
	v_mov_b32_e32 v80, v0
	v_mov_b32_e32 v81, v0
	v_mov_b32_e32 v82, v0
	v_mov_b32_e32 v83, v0
	v_mov_b32_e32 v84, v0
	v_mov_b32_e32 v85, v0
	v_mov_b32_e32 v86, v0
	v_mov_b32_e32 v87, v0
	v_mov_b32_e32 v96, v0
	v_mov_b32_e32 v97, v0
	v_mov_b32_e32 v98, v0
	v_mov_b32_e32 v99, v0
	v_mov_b32_e32 v100, v0
	v_mov_b32_e32 v101, v0
	v_mov_b32_e32 v102, v0
	v_mov_b32_e32 v103, v0
	v_mov_b32_e32 v112, v0
	v_mov_b32_e32 v113, v0
	v_mov_b32_e32 v114, v0
	v_mov_b32_e32 v115, v0
	v_mov_b32_e32 v116, v0
	v_mov_b32_e32 v117, v0
	v_mov_b32_e32 v118, v0
	v_mov_b32_e32 v119, v0
	v_mov_b32_e32 v72, v0
	v_mov_b32_e32 v73, v0
	v_mov_b32_e32 v74, v0
	v_mov_b32_e32 v75, v0
	v_mov_b32_e32 v76, v0
	v_mov_b32_e32 v77, v0
	v_mov_b32_e32 v78, v0
	v_mov_b32_e32 v79, v0
	v_mov_b32_e32 v88, v0
	v_mov_b32_e32 v89, v0
	v_mov_b32_e32 v90, v0
	v_mov_b32_e32 v91, v0
	v_mov_b32_e32 v92, v0
	v_mov_b32_e32 v93, v0
	v_mov_b32_e32 v94, v0
	v_mov_b32_e32 v95, v0
	v_mov_b32_e32 v104, v0
	v_mov_b32_e32 v105, v0
	v_mov_b32_e32 v106, v0
	v_mov_b32_e32 v107, v0
	v_mov_b32_e32 v108, v0
	v_mov_b32_e32 v109, v0
	v_mov_b32_e32 v110, v0
	v_mov_b32_e32 v111, v0
	v_mov_b32_e32 v120, v0
	v_mov_b32_e32 v121, v0
	v_mov_b32_e32 v122, v0
	v_mov_b32_e32 v123, v0
	v_mov_b32_e32 v124, v0
	v_mov_b32_e32 v125, v0
	v_mov_b32_e32 v126, v0
	v_mov_b32_e32 v127, v0
	.p2align	6

; template <class Epi, bool HALO>
; __device__ __forceinline__ void gemm_phase(LAS unsigned char* lds, const Gemm g, const StaticOrder& S, const Epi& E) {
;     ...
;         const char* nA = has_next ? A0 + (size_t)nxt.pm * tstepA + (size_t)nxt.pn * g.a_pn_off * 2 : cA; const char* nB = has_next ? (const char*)g.Bt + (size_t)nxt.pn * tstepB : cB;
;         for (int t = 0; t < nt; t += 2) {
;     ...
; #pragma unroll
;         for (int a = 0; a < 2; ++a)
; #pragma unroll
;             for (int b = 0; b < 2; ++b)
; #pragma unroll
;                 for (int m = 0; m < 4; ++m)
; #pragma unroll
;                     for (int n = 0; n < 2; ++n) acc[a][b][m][n] = (f32x4){0.f, 0.f, 0.f, 0.f};
;         cur = nxt; cA = nA; cB = nB; ++ui;
.LBB0_823:
	s_ashr_i32 s35, s34, 31
	s_lshl_b64 s[36:37], s[34:35], 19
	s_add_u32 s36, s60, s36
	s_addc_u32 s37, s61, s37
	s_and_b64 s[38:39], s[6:7], exec
	s_cselect_b32 s11, s37, s41
	s_cselect_b32 s16, s36, s40
	s_ashr_i32 s31, s30, 31
	s_lshl_b64 s[38:39], s[30:31], 19
	s_add_u32 s38, s56, s38
	s_addc_u32 s39, s57, s39
	s_and_b64 s[42:43], s[6:7], exec
	s_cselect_b32 s31, s39, s13
	s_cselect_b32 s35, s38, s12
	s_add_u32 s50, s12, 0x10000
	s_addc_u32 s51, s13, 0
	s_add_u32 s12, s40, 0x40080
	v_mov_b32_e32 v0, 0
	s_addc_u32 s13, s41, 0
	s_mov_b32 s52, -2
	v_mov_b32_e32 v1, v0
	v_mov_b32_e32 v2, v0
	v_mov_b32_e32 v3, v0
	v_mov_b32_e32 v4, v0
	v_mov_b32_e32 v5, v0
	v_mov_b32_e32 v6, v0
	v_mov_b32_e32 v7, v0
	s_waitcnt lgkmcnt(0)
	v_mov_b32_e32 v16, v0
	v_mov_b32_e32 v17, v0
	v_mov_b32_e32 v18, v0
	v_mov_b32_e32 v19, v0
	v_mov_b32_e32 v20, v0
	v_mov_b32_e32 v21, v0
	v_mov_b32_e32 v22, v0
	v_mov_b32_e32 v23, v0
	v_mov_b32_e32 v32, v0
	v_mov_b32_e32 v33, v0
	v_mov_b32_e32 v34, v0
	v_mov_b32_e32 v35, v0
	v_mov_b32_e32 v36, v0
	v_mov_b32_e32 v37, v0
	v_mov_b32_e32 v38, v0
	v_mov_b32_e32 v39, v0
	v_mov_b32_e32 v48, v0
	v_mov_b32_e32 v49, v0
	v_mov_b32_e32 v50, v0
	v_mov_b32_e32 v51, v0
	v_mov_b32_e32 v52, v0
	v_mov_b32_e32 v53, v0
	v_mov_b32_e32 v54, v0
	v_mov_b32_e32 v55, v0
	v_mov_b32_e32 v8, v0
	v_mov_b32_e32 v9, v0
	v_mov_b32_e32 v10, v0
	v_mov_b32_e32 v11, v0
	v_mov_b32_e32 v12, v0
	v_mov_b32_e32 v13, v0
	v_mov_b32_e32 v14, v0
	v_mov_b32_e32 v15, v0
	v_mov_b32_e32 v24, v0
	v_mov_b32_e32 v25, v0
	v_mov_b32_e32 v26, v0
	v_mov_b32_e32 v27, v0
	v_mov_b32_e32 v28, v0
	v_mov_b32_e32 v29, v0
	v_mov_b32_e32 v30, v0
	v_mov_b32_e32 v31, v0
	v_mov_b32_e32 v40, v0
	v_mov_b32_e32 v41, v0
	v_mov_b32_e32 v42, v0
	v_mov_b32_e32 v43, v0
	v_mov_b32_e32 v44, v0
	v_mov_b32_e32 v45, v0
	v_mov_b32_e32 v46, v0
	v_mov_b32_e32 v47, v0
	v_mov_b32_e32 v56, v0
	v_mov_b32_e32 v57, v0
	v_mov_b32_e32 v58, v0
	v_mov_b32_e32 v59, v0
	v_mov_b32_e32 v60, v0
	v_mov_b32_e32 v61, v0
	v_mov_b32_e32 v62, v0
	v_mov_b32_e32 v63, v0
	v_mov_b32_e32 v64, v0
	v_mov_b32_e32 v65, v0
	v_mov_b32_e32 v66, v0
	v_mov_b32_e32 v67, v0
	v_mov_b32_e32 v68, v0
	v_mov_b32_e32 v69, v0
	v_mov_b32_e32 v70, v0
	v_mov_b32_e32 v71, v0
	v_mov_b32_e32 v80, v0
	v_mov_b32_e32 v81, v0
	v_mov_b32_e32 v82, v0
	v_mov_b32_e32 v83, v0
	v_mov_b32_e32 v84, v0
	v_mov_b32_e32 v85, v0
	v_mov_b32_e32 v86, v0
	v_mov_b32_e32 v87, v0
	v_mov_b32_e32 v96, v0
	v_mov_b32_e32 v97, v0
	v_mov_b32_e32 v98, v0
	v_mov_b32_e32 v99, v0
	v_mov_b32_e32 v100, v0
	v_mov_b32_e32 v101, v0
	v_mov_b32_e32 v102, v0
	v_mov_b32_e32 v103, v0
	v_mov_b32_e32 v112, v0
	v_mov_b32_e32 v113, v0
	v_mov_b32_e32 v114, v0
	v_mov_b32_e32 v115, v0
	v_mov_b32_e32 v116, v0
	v_mov_b32_e32 v117, v0
	v_mov_b32_e32 v118, v0
	v_mov_b32_e32 v119, v0
	v_mov_b32_e32 v72, v0
	v_mov_b32_e32 v73, v0
	v_mov_b32_e32 v74, v0
	v_mov_b32_e32 v75, v0
	v_mov_b32_e32 v76, v0
	v_mov_b32_e32 v77, v0
	v_mov_b32_e32 v78, v0
	v_mov_b32_e32 v79, v0
	v_mov_b32_e32 v88, v0
	v_mov_b32_e32 v89, v0
	v_mov_b32_e32 v90, v0
	v_mov_b32_e32 v91, v0
	v_mov_b32_e32 v92, v0
	v_mov_b32_e32 v93, v0
	v_mov_b32_e32 v94, v0
	v_mov_b32_e32 v95, v0
	v_mov_b32_e32 v104, v0
	v_mov_b32_e32 v105, v0
	v_mov_b32_e32 v106, v0
	v_mov_b32_e32 v107, v0
	v_mov_b32_e32 v108, v0
	v_mov_b32_e32 v109, v0
	v_mov_b32_e32 v110, v0
	v_mov_b32_e32 v111, v0
	v_mov_b32_e32 v120, v0
	v_mov_b32_e32 v121, v0
	v_mov_b32_e32 v122, v0
	v_mov_b32_e32 v123, v0
	v_mov_b32_e32 v124, v0
	v_mov_b32_e32 v125, v0
	v_mov_b32_e32 v126, v0
	v_mov_b32_e32 v127, v0
	.p2align	6

; template <class Epi, bool HALO>
; __device__ __forceinline__ void gemm_phase(LAS unsigned char* lds, const Gemm g, const StaticOrder& S, const Epi& E) {
;     ...
;         const char* nA = has_next ? A0 + (size_t)nxt.pm * tstepA + (size_t)nxt.pn * g.a_pn_off * 2 : cA; const char* nB = has_next ? (const char*)g.Bt + (size_t)nxt.pn * tstepB : cB;
;         for (int t = 0; t < nt; t += 2) {
;     ...
; #pragma unroll
;         for (int a = 0; a < 2; ++a)
; #pragma unroll
;             for (int b = 0; b < 2; ++b)
; #pragma unroll
;                 for (int m = 0; m < 4; ++m)
; #pragma unroll
;                     for (int n = 0; n < 2; ++n) acc[a][b][m][n] = (f32x4){0.f, 0.f, 0.f, 0.f};
;         cur = nxt; cA = nA; cB = nB; ++ui;
.LBB0_1180:
	s_ashr_i32 s23, s22, 31
	s_lshl_b64 s[24:25], s[22:23], 19
	s_add_u32 s24, s40, s24
	s_addc_u32 s25, s41, s25
	s_and_b64 s[26:27], s[6:7], exec
	s_cselect_b32 s23, s25, s37
	s_cselect_b32 s29, s24, s36
	s_ashr_i32 s21, s20, 31
	s_lshl_b64 s[26:27], s[20:21], 19
	s_add_u32 s26, s42, s26
	s_addc_u32 s27, s43, s27
	s_and_b64 s[38:39], s[6:7], exec
	s_cselect_b32 s21, s27, s35
	s_cselect_b32 s31, s26, s34
	s_add_u32 s58, s34, 0x10000
	s_addc_u32 s59, s35, 0
	s_add_u32 s34, s36, 0x40080
	v_mov_b32_e32 v0, 0
	s_addc_u32 s35, s37, 0
	s_mov_b32 s60, -2
	s_waitcnt lgkmcnt(0)
	v_mov_b32_e32 v1, v0
	v_mov_b32_e32 v2, v0
	v_mov_b32_e32 v3, v0
	v_mov_b32_e32 v4, v0
	v_mov_b32_e32 v5, v0
	v_mov_b32_e32 v6, v0
	v_mov_b32_e32 v7, v0
	v_mov_b32_e32 v16, v0
	v_mov_b32_e32 v17, v0
	v_mov_b32_e32 v18, v0
	v_mov_b32_e32 v19, v0
	v_mov_b32_e32 v20, v0
	v_mov_b32_e32 v21, v0
	v_mov_b32_e32 v22, v0
	v_mov_b32_e32 v23, v0
	v_mov_b32_e32 v32, v0
	v_mov_b32_e32 v33, v0
	v_mov_b32_e32 v34, v0
	v_mov_b32_e32 v35, v0
	v_mov_b32_e32 v36, v0
	v_mov_b32_e32 v37, v0
	v_mov_b32_e32 v38, v0
	v_mov_b32_e32 v39, v0
	v_mov_b32_e32 v48, v0
	v_mov_b32_e32 v49, v0
	v_mov_b32_e32 v50, v0
	v_mov_b32_e32 v51, v0
	v_mov_b32_e32 v52, v0
	v_mov_b32_e32 v53, v0
	v_mov_b32_e32 v54, v0
	v_mov_b32_e32 v55, v0
	v_mov_b32_e32 v8, v0
	v_mov_b32_e32 v9, v0
	v_mov_b32_e32 v10, v0
	v_mov_b32_e32 v11, v0
	v_mov_b32_e32 v12, v0
	v_mov_b32_e32 v13, v0
	v_mov_b32_e32 v14, v0
	v_mov_b32_e32 v15, v0
	v_mov_b32_e32 v24, v0
	v_mov_b32_e32 v25, v0
	v_mov_b32_e32 v26, v0
	v_mov_b32_e32 v27, v0
	v_mov_b32_e32 v28, v0
	v_mov_b32_e32 v29, v0
	v_mov_b32_e32 v30, v0
	v_mov_b32_e32 v31, v0
	v_mov_b32_e32 v40, v0
	v_mov_b32_e32 v41, v0
	v_mov_b32_e32 v42, v0
	v_mov_b32_e32 v43, v0
	v_mov_b32_e32 v44, v0
	v_mov_b32_e32 v45, v0
	v_mov_b32_e32 v46, v0
	v_mov_b32_e32 v47, v0
	v_mov_b32_e32 v56, v0
	v_mov_b32_e32 v57, v0
	v_mov_b32_e32 v58, v0
	v_mov_b32_e32 v59, v0
	v_mov_b32_e32 v60, v0
	v_mov_b32_e32 v61, v0
	v_mov_b32_e32 v62, v0
	v_mov_b32_e32 v63, v0
	v_mov_b32_e32 v64, v0
	v_mov_b32_e32 v65, v0
	v_mov_b32_e32 v66, v0
	v_mov_b32_e32 v67, v0
	v_mov_b32_e32 v68, v0
	v_mov_b32_e32 v69, v0
	v_mov_b32_e32 v70, v0
	v_mov_b32_e32 v71, v0
	v_mov_b32_e32 v80, v0
	v_mov_b32_e32 v81, v0
	v_mov_b32_e32 v82, v0
	v_mov_b32_e32 v83, v0
	v_mov_b32_e32 v84, v0
	v_mov_b32_e32 v85, v0
	v_mov_b32_e32 v86, v0
	v_mov_b32_e32 v87, v0
	v_mov_b32_e32 v96, v0
	v_mov_b32_e32 v97, v0
	v_mov_b32_e32 v98, v0
	v_mov_b32_e32 v99, v0
	v_mov_b32_e32 v100, v0
	v_mov_b32_e32 v101, v0
	v_mov_b32_e32 v102, v0
	v_mov_b32_e32 v103, v0
	v_mov_b32_e32 v112, v0
	v_mov_b32_e32 v113, v0
	v_mov_b32_e32 v114, v0
	v_mov_b32_e32 v115, v0
	v_mov_b32_e32 v116, v0
	v_mov_b32_e32 v117, v0
	v_mov_b32_e32 v118, v0
	v_mov_b32_e32 v119, v0
	v_mov_b32_e32 v72, v0
	v_mov_b32_e32 v73, v0
	v_mov_b32_e32 v74, v0
	v_mov_b32_e32 v75, v0
	v_mov_b32_e32 v76, v0
	v_mov_b32_e32 v77, v0
	v_mov_b32_e32 v78, v0
	v_mov_b32_e32 v79, v0
	v_mov_b32_e32 v88, v0
	v_mov_b32_e32 v89, v0
	v_mov_b32_e32 v90, v0
	v_mov_b32_e32 v91, v0
	v_mov_b32_e32 v92, v0
	v_mov_b32_e32 v93, v0
	v_mov_b32_e32 v94, v0
	v_mov_b32_e32 v95, v0
	v_mov_b32_e32 v104, v0
	v_mov_b32_e32 v105, v0
	v_mov_b32_e32 v106, v0
	v_mov_b32_e32 v107, v0
	v_mov_b32_e32 v108, v0
	v_mov_b32_e32 v109, v0
	v_mov_b32_e32 v110, v0
	v_mov_b32_e32 v111, v0
	v_mov_b32_e32 v120, v0
	v_mov_b32_e32 v121, v0
	v_mov_b32_e32 v122, v0
	v_mov_b32_e32 v123, v0
	v_mov_b32_e32 v124, v0
	v_mov_b32_e32 v125, v0
	v_mov_b32_e32 v126, v0
	v_mov_b32_e32 v127, v0
	.p2align	6

; template <class Epi, bool HALO>
; __device__ __forceinline__ void gemm_phase(LAS unsigned char* lds, const Gemm g, const StaticOrder& S, const Epi& E) {
;     ...
;         const char* nA = has_next ? A0 + (size_t)nxt.pm * tstepA + (size_t)nxt.pn * g.a_pn_off * 2 : cA; const char* nB = has_next ? (const char*)g.Bt + (size_t)nxt.pn * tstepB : cB;
;         for (int t = 0; t < nt; t += 2) {
;     ...
; #pragma unroll
;         for (int a = 0; a < 2; ++a)
; #pragma unroll
;             for (int b = 0; b < 2; ++b)
; #pragma unroll
;                 for (int m = 0; m < 4; ++m)
; #pragma unroll
;                     for (int n = 0; n < 2; ++n) acc[a][b][m][n] = (f32x4){0.f, 0.f, 0.f, 0.f};
;         cur = nxt; cA = nA; cB = nB; ++ui;
.LBB0_1406:
	s_add_u32 s16, s16, 0xc000
	s_addc_u32 s17, s17, 0
	s_add_u32 s45, s18, 0x10000
	v_mov_b32_e32 v0, 0
	s_addc_u32 s46, s19, 0
	s_mov_b32 s47, -2
	v_mov_b32_e32 v1, v0
	v_mov_b32_e32 v2, v0
	v_mov_b32_e32 v3, v0
	v_mov_b32_e32 v4, v0
	v_mov_b32_e32 v5, v0
	v_mov_b32_e32 v6, v0
	v_mov_b32_e32 v7, v0
	v_mov_b32_e32 v16, v0
	v_mov_b32_e32 v17, v0
	v_mov_b32_e32 v18, v0
	v_mov_b32_e32 v19, v0
	v_mov_b32_e32 v20, v0
	v_mov_b32_e32 v21, v0
	v_mov_b32_e32 v22, v0
	v_mov_b32_e32 v23, v0
	v_mov_b32_e32 v32, v0
	v_mov_b32_e32 v33, v0
	v_mov_b32_e32 v34, v0
	v_mov_b32_e32 v35, v0
	v_mov_b32_e32 v36, v0
	v_mov_b32_e32 v37, v0
	v_mov_b32_e32 v38, v0
	v_mov_b32_e32 v39, v0
	v_mov_b32_e32 v48, v0
	v_mov_b32_e32 v49, v0
	v_mov_b32_e32 v50, v0
	v_mov_b32_e32 v51, v0
	v_mov_b32_e32 v52, v0
	v_mov_b32_e32 v53, v0
	v_mov_b32_e32 v54, v0
	v_mov_b32_e32 v55, v0
	v_mov_b32_e32 v8, v0
	v_mov_b32_e32 v9, v0
	v_mov_b32_e32 v10, v0
	v_mov_b32_e32 v11, v0
	v_mov_b32_e32 v12, v0
	v_mov_b32_e32 v13, v0
	v_mov_b32_e32 v14, v0
	v_mov_b32_e32 v15, v0
	v_mov_b32_e32 v24, v0
	v_mov_b32_e32 v25, v0
	v_mov_b32_e32 v26, v0
	v_mov_b32_e32 v27, v0
	v_mov_b32_e32 v28, v0
	v_mov_b32_e32 v29, v0
	v_mov_b32_e32 v30, v0
	v_mov_b32_e32 v31, v0
	v_mov_b32_e32 v40, v0
	v_mov_b32_e32 v41, v0
	v_mov_b32_e32 v42, v0
	v_mov_b32_e32 v43, v0
	v_mov_b32_e32 v44, v0
	v_mov_b32_e32 v45, v0
	v_mov_b32_e32 v46, v0
	v_mov_b32_e32 v47, v0
	v_mov_b32_e32 v56, v0
	v_mov_b32_e32 v57, v0
	v_mov_b32_e32 v58, v0
	v_mov_b32_e32 v59, v0
	v_mov_b32_e32 v60, v0
	v_mov_b32_e32 v61, v0
	v_mov_b32_e32 v62, v0
	v_mov_b32_e32 v63, v0
	v_mov_b32_e32 v64, v0
	v_mov_b32_e32 v65, v0
	v_mov_b32_e32 v66, v0
	v_mov_b32_e32 v67, v0
	v_mov_b32_e32 v68, v0
	v_mov_b32_e32 v69, v0
	v_mov_b32_e32 v70, v0
	v_mov_b32_e32 v71, v0
	v_mov_b32_e32 v80, v0
	v_mov_b32_e32 v81, v0
	v_mov_b32_e32 v82, v0
	v_mov_b32_e32 v83, v0
	v_mov_b32_e32 v84, v0
	v_mov_b32_e32 v85, v0
	v_mov_b32_e32 v86, v0
	v_mov_b32_e32 v87, v0
	v_mov_b32_e32 v96, v0
	v_mov_b32_e32 v97, v0
	v_mov_b32_e32 v98, v0
	v_mov_b32_e32 v99, v0
	v_mov_b32_e32 v100, v0
	v_mov_b32_e32 v101, v0
	v_mov_b32_e32 v102, v0
	v_mov_b32_e32 v103, v0
	v_mov_b32_e32 v112, v0
	v_mov_b32_e32 v113, v0
	v_mov_b32_e32 v114, v0
	v_mov_b32_e32 v115, v0
	v_mov_b32_e32 v116, v0
	v_mov_b32_e32 v117, v0
	v_mov_b32_e32 v118, v0
	v_mov_b32_e32 v119, v0
	v_mov_b32_e32 v72, v0
	v_mov_b32_e32 v73, v0
	v_mov_b32_e32 v74, v0
	v_mov_b32_e32 v75, v0
	v_mov_b32_e32 v76, v0
	v_mov_b32_e32 v77, v0
	v_mov_b32_e32 v78, v0
	v_mov_b32_e32 v79, v0
	v_mov_b32_e32 v88, v0
	v_mov_b32_e32 v89, v0
	v_mov_b32_e32 v90, v0
	v_mov_b32_e32 v91, v0
	v_mov_b32_e32 v92, v0
	v_mov_b32_e32 v93, v0
	v_mov_b32_e32 v94, v0
	v_mov_b32_e32 v95, v0
	v_mov_b32_e32 v104, v0
	v_mov_b32_e32 v105, v0
	v_mov_b32_e32 v106, v0
	v_mov_b32_e32 v107, v0
	v_mov_b32_e32 v108, v0
	v_mov_b32_e32 v109, v0
	v_mov_b32_e32 v110, v0
	v_mov_b32_e32 v111, v0
	v_mov_b32_e32 v120, v0
	v_mov_b32_e32 v121, v0
	v_mov_b32_e32 v122, v0
	v_mov_b32_e32 v123, v0
	v_mov_b32_e32 v124, v0
	v_mov_b32_e32 v125, v0
	v_mov_b32_e32 v126, v0
	v_mov_b32_e32 v127, v0
	.p2align	6
